# tail row panel: padding rows (128..255) no longer stored by the straight-line epilogues of P1/P5/P7/P9
# speedup vs baseline: 1.0013x; 1.0013x over previous
.LBB0_210:
	s_cmp_lg_u32 s96, 0
	s_cbranch_scc1 .Lp1_epi_other
	v_lshl_add_u32 v2, s60, 8, v224
	s_waitcnt lgkmcnt(0)
	s_mov_b64 s[6:7], 0x100000
	v_lshl_or_b32 v132, s56, 8, v234
	v_bfe_u32 v138, v234, 2, 1
	v_mul_u32_u24_e32 v138, 24, v138
	v_lshl_add_u32 v136, v132, 1, v138
	v_mov_b32_e32 v137, 0
	v_ashrrev_i32_e32 v3, 31, v2
	v_lshlrev_b64 v[140:141], 13, v[2:3]
	v_lshl_add_u64 v[140:141], s[26:27], 0, v[140:141]
	v_lshl_add_u64 v[140:141], v[140:141], 0, v[136:137]
	v_or_b32_e32 v142, 16, v2
	v_ashrrev_i32_e32 v143, 31, v142
	v_lshlrev_b64 v[142:143], 13, v[142:143]
	v_lshl_add_u64 v[142:143], s[26:27], 0, v[142:143]
	v_lshl_add_u64 v[142:143], v[142:143], 0, v[136:137]
	v_or_b32_e32 v144, 32, v2
	v_ashrrev_i32_e32 v145, 31, v144
	v_lshlrev_b64 v[144:145], 13, v[144:145]
	v_lshl_add_u64 v[144:145], s[26:27], 0, v[144:145]
	v_lshl_add_u64 v[144:145], v[144:145], 0, v[136:137]
	v_or_b32_e32 v146, 48, v2
	v_ashrrev_i32_e32 v147, 31, v146
	v_lshlrev_b64 v[146:147], 13, v[146:147]
	v_lshl_add_u64 v[146:147], s[26:27], 0, v[146:147]
	v_lshl_add_u64 v[146:147], v[146:147], 0, v[136:137]
	v_lshl_add_u64 v[148:149], v[140:141], 0, s[6:7]
	v_lshl_add_u64 v[150:151], v[142:143], 0, s[6:7]
	v_lshl_add_u64 v[152:153], v[144:145], 0, s[6:7]
	v_lshl_add_u64 v[154:155], v[146:147], 0, s[6:7]
	s_nop 7
	v_cvt_pk_bf16_f32 v128, v128, v129
	v_cvt_pk_bf16_f32 v129, v130, v131
	v_cvt_pk_bf16_f32 v130, v124, v125
	v_cvt_pk_bf16_f32 v131, v126, v127
	v_cvt_pk_bf16_f32 v120, v120, v121
	v_cvt_pk_bf16_f32 v121, v122, v123
	v_cvt_pk_bf16_f32 v122, v116, v117
	v_cvt_pk_bf16_f32 v123, v118, v119
	s_nop 1
	v_permlane16_swap_b32_e32 v128, v130
	v_permlane16_swap_b32_e32 v129, v131
	v_permlane16_swap_b32_e32 v120, v122
	v_permlane16_swap_b32_e32 v121, v123
	global_store_dwordx4 v[140:141], v[128:131], off
	global_store_dwordx4 v[140:141], v[120:123], off offset:256
	v_cvt_pk_bf16_f32 v112, v112, v113
	v_cvt_pk_bf16_f32 v113, v114, v115
	v_cvt_pk_bf16_f32 v114, v108, v109
	v_cvt_pk_bf16_f32 v115, v110, v111
	v_cvt_pk_bf16_f32 v104, v104, v105
	v_cvt_pk_bf16_f32 v105, v106, v107
	v_cvt_pk_bf16_f32 v106, v100, v101
	v_cvt_pk_bf16_f32 v107, v102, v103
	s_nop 1
	v_permlane16_swap_b32_e32 v112, v114
	v_permlane16_swap_b32_e32 v113, v115
	v_permlane16_swap_b32_e32 v104, v106
	v_permlane16_swap_b32_e32 v105, v107
	global_store_dwordx4 v[142:143], v[112:115], off
	global_store_dwordx4 v[142:143], v[104:107], off offset:256
	v_cvt_pk_bf16_f32 v96, v96, v97
	v_cvt_pk_bf16_f32 v97, v98, v99
	v_cvt_pk_bf16_f32 v98, v92, v93
	v_cvt_pk_bf16_f32 v99, v94, v95
	v_cvt_pk_bf16_f32 v88, v88, v89
	v_cvt_pk_bf16_f32 v89, v90, v91
	v_cvt_pk_bf16_f32 v90, v84, v85
	v_cvt_pk_bf16_f32 v91, v86, v87
	s_nop 1
	v_permlane16_swap_b32_e32 v96, v98
	v_permlane16_swap_b32_e32 v97, v99
	v_permlane16_swap_b32_e32 v88, v90
	v_permlane16_swap_b32_e32 v89, v91
	global_store_dwordx4 v[144:145], v[96:99], off
	global_store_dwordx4 v[144:145], v[88:91], off offset:256
	v_cvt_pk_bf16_f32 v80, v80, v81
	v_cvt_pk_bf16_f32 v81, v82, v83
	v_cvt_pk_bf16_f32 v82, v76, v77
	v_cvt_pk_bf16_f32 v83, v78, v79
	v_cvt_pk_bf16_f32 v72, v72, v73
	v_cvt_pk_bf16_f32 v73, v74, v75
	v_cvt_pk_bf16_f32 v74, v68, v69
	v_cvt_pk_bf16_f32 v75, v70, v71
	s_nop 1
	v_permlane16_swap_b32_e32 v80, v82
	v_permlane16_swap_b32_e32 v81, v83
	v_permlane16_swap_b32_e32 v72, v74
	v_permlane16_swap_b32_e32 v73, v75
	global_store_dwordx4 v[146:147], v[80:83], off
	global_store_dwordx4 v[146:147], v[72:75], off offset:256
	s_cmp_eq_u32 s60, 64
	s_cbranch_scc1 .Lp1e_nopad
	v_cvt_pk_bf16_f32 v64, v64, v65
	v_cvt_pk_bf16_f32 v65, v66, v67
	v_cvt_pk_bf16_f32 v66, v60, v61
	v_cvt_pk_bf16_f32 v67, v62, v63
	v_cvt_pk_bf16_f32 v56, v56, v57
	v_cvt_pk_bf16_f32 v57, v58, v59
	v_cvt_pk_bf16_f32 v58, v52, v53
	v_cvt_pk_bf16_f32 v59, v54, v55
	s_nop 1
	v_permlane16_swap_b32_e32 v64, v66
	v_permlane16_swap_b32_e32 v65, v67
	v_permlane16_swap_b32_e32 v56, v58
	v_permlane16_swap_b32_e32 v57, v59
	global_store_dwordx4 v[148:149], v[64:67], off
	global_store_dwordx4 v[148:149], v[56:59], off offset:256
	v_cvt_pk_bf16_f32 v48, v48, v49
	v_cvt_pk_bf16_f32 v49, v50, v51
	v_cvt_pk_bf16_f32 v50, v44, v45
	v_cvt_pk_bf16_f32 v51, v46, v47
	v_cvt_pk_bf16_f32 v40, v40, v41
	v_cvt_pk_bf16_f32 v41, v42, v43
	v_cvt_pk_bf16_f32 v42, v36, v37
	v_cvt_pk_bf16_f32 v43, v38, v39
	s_nop 1
	v_permlane16_swap_b32_e32 v48, v50
	v_permlane16_swap_b32_e32 v49, v51
	v_permlane16_swap_b32_e32 v40, v42
	v_permlane16_swap_b32_e32 v41, v43
	global_store_dwordx4 v[150:151], v[48:51], off
	global_store_dwordx4 v[150:151], v[40:43], off offset:256
	v_cvt_pk_bf16_f32 v32, v32, v33
	v_cvt_pk_bf16_f32 v33, v34, v35
	v_cvt_pk_bf16_f32 v34, v28, v29
	v_cvt_pk_bf16_f32 v35, v30, v31
	v_cvt_pk_bf16_f32 v24, v24, v25
	v_cvt_pk_bf16_f32 v25, v26, v27
	v_cvt_pk_bf16_f32 v26, v20, v21
	v_cvt_pk_bf16_f32 v27, v22, v23
	s_nop 1
	v_permlane16_swap_b32_e32 v32, v34
	v_permlane16_swap_b32_e32 v33, v35
	v_permlane16_swap_b32_e32 v24, v26
	v_permlane16_swap_b32_e32 v25, v27
	global_store_dwordx4 v[152:153], v[32:35], off
	global_store_dwordx4 v[152:153], v[24:27], off offset:256
	v_cvt_pk_bf16_f32 v16, v16, v17
	v_cvt_pk_bf16_f32 v17, v18, v19
	v_cvt_pk_bf16_f32 v18, v12, v13
	v_cvt_pk_bf16_f32 v19, v14, v15
	v_cvt_pk_bf16_f32 v8, v8, v9
	v_cvt_pk_bf16_f32 v9, v10, v11
	v_cvt_pk_bf16_f32 v10, v4, v5
	v_cvt_pk_bf16_f32 v11, v6, v7
	s_nop 1
	v_permlane16_swap_b32_e32 v16, v18
	v_permlane16_swap_b32_e32 v17, v19
	v_permlane16_swap_b32_e32 v8, v10
	v_permlane16_swap_b32_e32 v9, v11
	global_store_dwordx4 v[154:155], v[16:19], off
	global_store_dwordx4 v[154:155], v[8:11], off offset:256
.Lp1e_nopad:
	s_branch .LBB0_187
.Lp1_epi_other:
	s_lshl_b32 s41, s56, 8
	s_cmp_lg_u32 s96, 0
	s_waitcnt lgkmcnt(0)
	v_lshl_add_u32 v136, s60, 8, v224
	s_cselect_b64 s[60:61], -1, 0
	s_bfe_u32 s6, s56, 0x10001
	s_lshl_b32 s45, s6, 2
	v_ashrrev_i32_e32 v0, 8, v136
	v_add_u32_e32 v2, s45, v0
	v_ashrrev_i32_e32 v3, 31, v2
	s_lshl_b32 s64, s6, 3
	v_lshlrev_b64 v[140:141], 19, v[2:3]
	v_add_u32_e32 v2, s64, v2
	v_ashrrev_i32_e32 v3, 31, v2
	v_lshlrev_b64 v[138:139], 18, v[2:3]
	v_or_b32_e32 v2, s41, v234
	v_and_b32_e32 v0, 0x16c, v2
	s_and_b64 vcc, exec, s[60:61]
	v_lshlrev_b32_e32 v134, 2, v0
	v_cvt_pk_bf16_f32 v144, v128, v129
	v_cvt_pk_bf16_f32 v145, v130, v131
	v_lshlrev_b32_e32 v132, 1, v0
	s_cbranch_vccz .LBB0_212
	s_cmpk_lt_u32 s41, 0x400
	s_cselect_b32 s56, s91, 0x14710000
	s_cselect_b32 s7, s74, s33
	s_cselect_b32 s6, s35, s3
	s_add_u32 s56, s48, s56
	s_addc_u32 s57, s49, 0
	v_lshl_add_u64 v[142:143], s[56:57], 0, v[140:141]
	v_lshl_add_u64 v[142:143], v[142:143], 0, v[206:207]
	v_mov_b32_e32 v135, v1
	v_lshl_add_u64 v[142:143], v[142:143], 0, v[134:135]
	global_store_dwordx4 v[142:143], v[128:131], off
	v_mov_b32_e32 v133, v1
	s_nop 0
	v_lshl_add_u64 v[128:129], s[6:7], 0, v[138:139]
	v_lshl_add_u64 v[128:129], v[128:129], 0, v[208:209]
	v_lshl_add_u64 v[128:129], v[128:129], 0, v[132:133]
	global_store_dwordx2 v[128:129], v[144:145], off
	s_mov_b64 s[6:7], 0
	s_branch .LBB0_213

.LBB0_477:
	v_lshl_add_u32 v2, s58, 8, v224
	s_waitcnt lgkmcnt(0)
	v_lshl_or_b32 v132, s90, 8, v240
	v_bfe_u32 v138, v240, 2, 1
	v_mul_u32_u24_e32 v138, 24, v138
	v_lshl_add_u32 v136, v132, 1, v138
	v_mov_b32_e32 v137, 0
	v_ashrrev_i32_e32 v3, 31, v2
	v_lshlrev_b64 v[140:141], 12, v[2:3]
	v_lshl_add_u64 v[140:141], s[26:27], 0, v[140:141]
	v_lshl_add_u64 v[140:141], v[140:141], 0, v[136:137]
	v_or_b32_e32 v142, 16, v2
	v_ashrrev_i32_e32 v143, 31, v142
	v_lshlrev_b64 v[142:143], 12, v[142:143]
	v_lshl_add_u64 v[142:143], s[26:27], 0, v[142:143]
	v_lshl_add_u64 v[142:143], v[142:143], 0, v[136:137]
	v_or_b32_e32 v144, 32, v2
	v_ashrrev_i32_e32 v145, 31, v144
	v_lshlrev_b64 v[144:145], 12, v[144:145]
	v_lshl_add_u64 v[144:145], s[26:27], 0, v[144:145]
	v_lshl_add_u64 v[144:145], v[144:145], 0, v[136:137]
	v_or_b32_e32 v146, 48, v2
	v_ashrrev_i32_e32 v147, 31, v146
	v_lshlrev_b64 v[146:147], 12, v[146:147]
	v_lshl_add_u64 v[146:147], s[26:27], 0, v[146:147]
	v_lshl_add_u64 v[146:147], v[146:147], 0, v[136:137]
	v_lshl_add_u64 v[148:149], v[140:141], 0, s[8:9]
	v_lshl_add_u64 v[150:151], v[142:143], 0, s[8:9]
	v_lshl_add_u64 v[152:153], v[144:145], 0, s[8:9]
	v_lshl_add_u64 v[154:155], v[146:147], 0, s[8:9]
	s_nop 7
	v_cvt_pk_bf16_f32 v128, v128, v129
	v_cvt_pk_bf16_f32 v129, v130, v131
	v_cvt_pk_bf16_f32 v130, v124, v125
	v_cvt_pk_bf16_f32 v131, v126, v127
	v_cvt_pk_bf16_f32 v116, v116, v117
	v_cvt_pk_bf16_f32 v117, v118, v119
	v_cvt_pk_bf16_f32 v118, v108, v109
	v_cvt_pk_bf16_f32 v119, v110, v111
	s_nop 1
	v_permlane16_swap_b32_e32 v128, v130
	v_permlane16_swap_b32_e32 v129, v131
	v_permlane16_swap_b32_e32 v116, v118
	v_permlane16_swap_b32_e32 v117, v119
	global_store_dwordx4 v[140:141], v[128:131], off
	global_store_dwordx4 v[140:141], v[116:119], off offset:256
	v_cvt_pk_bf16_f32 v120, v120, v121
	v_cvt_pk_bf16_f32 v121, v122, v123
	v_cvt_pk_bf16_f32 v122, v112, v113
	v_cvt_pk_bf16_f32 v123, v114, v115
	v_cvt_pk_bf16_f32 v100, v100, v101
	v_cvt_pk_bf16_f32 v101, v102, v103
	v_cvt_pk_bf16_f32 v102, v92, v93
	v_cvt_pk_bf16_f32 v103, v94, v95
	s_nop 1
	v_permlane16_swap_b32_e32 v120, v122
	v_permlane16_swap_b32_e32 v121, v123
	v_permlane16_swap_b32_e32 v100, v102
	v_permlane16_swap_b32_e32 v101, v103
	global_store_dwordx4 v[142:143], v[120:123], off
	global_store_dwordx4 v[142:143], v[100:103], off offset:256
	v_cvt_pk_bf16_f32 v104, v104, v105
	v_cvt_pk_bf16_f32 v105, v106, v107
	v_cvt_pk_bf16_f32 v106, v96, v97
	v_cvt_pk_bf16_f32 v107, v98, v99
	v_cvt_pk_bf16_f32 v84, v84, v85
	v_cvt_pk_bf16_f32 v85, v86, v87
	v_cvt_pk_bf16_f32 v86, v76, v77
	v_cvt_pk_bf16_f32 v87, v78, v79
	s_nop 1
	v_permlane16_swap_b32_e32 v104, v106
	v_permlane16_swap_b32_e32 v105, v107
	v_permlane16_swap_b32_e32 v84, v86
	v_permlane16_swap_b32_e32 v85, v87
	global_store_dwordx4 v[144:145], v[104:107], off
	global_store_dwordx4 v[144:145], v[84:87], off offset:256
	v_cvt_pk_bf16_f32 v88, v88, v89
	v_cvt_pk_bf16_f32 v89, v90, v91
	v_cvt_pk_bf16_f32 v90, v80, v81
	v_cvt_pk_bf16_f32 v91, v82, v83
	v_cvt_pk_bf16_f32 v72, v72, v73
	v_cvt_pk_bf16_f32 v73, v74, v75
	v_cvt_pk_bf16_f32 v74, v68, v69
	v_cvt_pk_bf16_f32 v75, v70, v71
	s_nop 1
	v_permlane16_swap_b32_e32 v88, v90
	v_permlane16_swap_b32_e32 v89, v91
	v_permlane16_swap_b32_e32 v72, v74
	v_permlane16_swap_b32_e32 v73, v75
	global_store_dwordx4 v[146:147], v[88:91], off
	global_store_dwordx4 v[146:147], v[72:75], off offset:256
	s_cmp_eq_u32 s58, 64
	s_cbranch_scc1 .Lp5e_nopad
	v_cvt_pk_bf16_f32 v64, v64, v65
	v_cvt_pk_bf16_f32 v65, v66, v67
	v_cvt_pk_bf16_f32 v66, v60, v61
	v_cvt_pk_bf16_f32 v67, v62, v63
	v_cvt_pk_bf16_f32 v56, v56, v57
	v_cvt_pk_bf16_f32 v57, v58, v59
	v_cvt_pk_bf16_f32 v58, v48, v49
	v_cvt_pk_bf16_f32 v59, v50, v51
	s_nop 1
	v_permlane16_swap_b32_e32 v64, v66
	v_permlane16_swap_b32_e32 v65, v67
	v_permlane16_swap_b32_e32 v56, v58
	v_permlane16_swap_b32_e32 v57, v59
	global_store_dwordx4 v[148:149], v[64:67], off
	global_store_dwordx4 v[148:149], v[56:59], off offset:256
	v_cvt_pk_bf16_f32 v52, v52, v53
	v_cvt_pk_bf16_f32 v53, v54, v55
	v_cvt_pk_bf16_f32 v54, v44, v45
	v_cvt_pk_bf16_f32 v55, v46, v47
	v_cvt_pk_bf16_f32 v40, v40, v41
	v_cvt_pk_bf16_f32 v41, v42, v43
	v_cvt_pk_bf16_f32 v42, v32, v33
	v_cvt_pk_bf16_f32 v43, v34, v35
	s_nop 1
	v_permlane16_swap_b32_e32 v52, v54
	v_permlane16_swap_b32_e32 v53, v55
	v_permlane16_swap_b32_e32 v40, v42
	v_permlane16_swap_b32_e32 v41, v43
	global_store_dwordx4 v[150:151], v[52:55], off
	global_store_dwordx4 v[150:151], v[40:43], off offset:256
	v_cvt_pk_bf16_f32 v36, v36, v37
	v_cvt_pk_bf16_f32 v37, v38, v39
	v_cvt_pk_bf16_f32 v38, v28, v29
	v_cvt_pk_bf16_f32 v39, v30, v31
	v_cvt_pk_bf16_f32 v24, v24, v25
	v_cvt_pk_bf16_f32 v25, v26, v27
	v_cvt_pk_bf16_f32 v26, v16, v17
	v_cvt_pk_bf16_f32 v27, v18, v19
	s_nop 1
	v_permlane16_swap_b32_e32 v36, v38
	v_permlane16_swap_b32_e32 v37, v39
	v_permlane16_swap_b32_e32 v24, v26
	v_permlane16_swap_b32_e32 v25, v27
	global_store_dwordx4 v[152:153], v[36:39], off
	global_store_dwordx4 v[152:153], v[24:27], off offset:256
	v_cvt_pk_bf16_f32 v20, v20, v21
	v_cvt_pk_bf16_f32 v21, v22, v23
	v_cvt_pk_bf16_f32 v22, v12, v13
	v_cvt_pk_bf16_f32 v23, v14, v15
	v_cvt_pk_bf16_f32 v8, v8, v9
	v_cvt_pk_bf16_f32 v9, v10, v11
	v_cvt_pk_bf16_f32 v10, v4, v5
	v_cvt_pk_bf16_f32 v11, v6, v7
	s_nop 1
	v_permlane16_swap_b32_e32 v20, v22
	v_permlane16_swap_b32_e32 v21, v23
	v_permlane16_swap_b32_e32 v8, v10
	v_permlane16_swap_b32_e32 v9, v11
	global_store_dwordx4 v[154:155], v[20:23], off
	global_store_dwordx4 v[154:155], v[8:11], off offset:256
.Lp5e_nopad:
	s_and_b64 vcc, exec, s[44:45]
	s_mov_b32 s90, s89
	s_mov_b32 s58, s46
	s_mov_b64 s[70:71], s[54:55]
	s_mov_b64 s[6:7], s[56:57]
	s_cbranch_vccnz .LBB0_494

.LBB0_555:
	s_waitcnt lgkmcnt(0)
	s_cmp_lt_u32 s58, 12
	s_cbranch_scc1 .Lp7_epi_kv
	v_lshl_add_u32 v2, s10, 8, v240
	s_mov_b64 s[12:13], 0x100000
	v_lshl_or_b32 v132, s58, 8, v242
	v_bfe_u32 v138, v242, 2, 1
	v_mul_u32_u24_e32 v138, 24, v138
	v_lshl_add_u32 v136, v132, 1, v138
	v_subrev_u32_e32 v136, 6144, v136
	v_mov_b32_e32 v137, 0
	v_ashrrev_i32_e32 v3, 31, v2
	v_lshlrev_b64 v[140:141], 13, v[2:3]
	v_lshl_add_u64 v[140:141], s[26:27], 0, v[140:141]
	v_lshl_add_u64 v[140:141], v[140:141], 0, v[136:137]
	v_or_b32_e32 v142, 16, v2
	v_ashrrev_i32_e32 v143, 31, v142
	v_lshlrev_b64 v[142:143], 13, v[142:143]
	v_lshl_add_u64 v[142:143], s[26:27], 0, v[142:143]
	v_lshl_add_u64 v[142:143], v[142:143], 0, v[136:137]
	v_or_b32_e32 v144, 32, v2
	v_ashrrev_i32_e32 v145, 31, v144
	v_lshlrev_b64 v[144:145], 13, v[144:145]
	v_lshl_add_u64 v[144:145], s[26:27], 0, v[144:145]
	v_lshl_add_u64 v[144:145], v[144:145], 0, v[136:137]
	v_or_b32_e32 v146, 48, v2
	v_ashrrev_i32_e32 v147, 31, v146
	v_lshlrev_b64 v[146:147], 13, v[146:147]
	v_lshl_add_u64 v[146:147], s[26:27], 0, v[146:147]
	v_lshl_add_u64 v[146:147], v[146:147], 0, v[136:137]
	v_lshl_add_u64 v[148:149], v[140:141], 0, s[12:13]
	v_lshl_add_u64 v[150:151], v[142:143], 0, s[12:13]
	v_lshl_add_u64 v[152:153], v[144:145], 0, s[12:13]
	v_lshl_add_u64 v[154:155], v[146:147], 0, s[12:13]
	s_nop 7
	v_cvt_pk_bf16_f32 v128, v128, v129
	v_cvt_pk_bf16_f32 v129, v130, v131
	v_cvt_pk_bf16_f32 v130, v124, v125
	v_cvt_pk_bf16_f32 v131, v126, v127
	v_cvt_pk_bf16_f32 v120, v120, v121
	v_cvt_pk_bf16_f32 v121, v122, v123
	v_cvt_pk_bf16_f32 v122, v116, v117
	v_cvt_pk_bf16_f32 v123, v118, v119
	s_nop 1
	v_permlane16_swap_b32_e32 v128, v130
	v_permlane16_swap_b32_e32 v129, v131
	v_permlane16_swap_b32_e32 v120, v122
	v_permlane16_swap_b32_e32 v121, v123
	global_store_dwordx4 v[140:141], v[128:131], off
	global_store_dwordx4 v[140:141], v[120:123], off offset:256
	v_cvt_pk_bf16_f32 v112, v112, v113
	v_cvt_pk_bf16_f32 v113, v114, v115
	v_cvt_pk_bf16_f32 v114, v108, v109
	v_cvt_pk_bf16_f32 v115, v110, v111
	v_cvt_pk_bf16_f32 v104, v104, v105
	v_cvt_pk_bf16_f32 v105, v106, v107
	v_cvt_pk_bf16_f32 v106, v100, v101
	v_cvt_pk_bf16_f32 v107, v102, v103
	s_nop 1
	v_permlane16_swap_b32_e32 v112, v114
	v_permlane16_swap_b32_e32 v113, v115
	v_permlane16_swap_b32_e32 v104, v106
	v_permlane16_swap_b32_e32 v105, v107
	global_store_dwordx4 v[142:143], v[112:115], off
	global_store_dwordx4 v[142:143], v[104:107], off offset:256
	v_cvt_pk_bf16_f32 v96, v96, v97
	v_cvt_pk_bf16_f32 v97, v98, v99
	v_cvt_pk_bf16_f32 v98, v92, v93
	v_cvt_pk_bf16_f32 v99, v94, v95
	v_cvt_pk_bf16_f32 v88, v88, v89
	v_cvt_pk_bf16_f32 v89, v90, v91
	v_cvt_pk_bf16_f32 v90, v84, v85
	v_cvt_pk_bf16_f32 v91, v86, v87
	s_nop 1
	v_permlane16_swap_b32_e32 v96, v98
	v_permlane16_swap_b32_e32 v97, v99
	v_permlane16_swap_b32_e32 v88, v90
	v_permlane16_swap_b32_e32 v89, v91
	global_store_dwordx4 v[144:145], v[96:99], off
	global_store_dwordx4 v[144:145], v[88:91], off offset:256
	v_cvt_pk_bf16_f32 v80, v80, v81
	v_cvt_pk_bf16_f32 v81, v82, v83
	v_cvt_pk_bf16_f32 v82, v76, v77
	v_cvt_pk_bf16_f32 v83, v78, v79
	v_cvt_pk_bf16_f32 v72, v72, v73
	v_cvt_pk_bf16_f32 v73, v74, v75
	v_cvt_pk_bf16_f32 v74, v68, v69
	v_cvt_pk_bf16_f32 v75, v70, v71
	s_nop 1
	v_permlane16_swap_b32_e32 v80, v82
	v_permlane16_swap_b32_e32 v81, v83
	v_permlane16_swap_b32_e32 v72, v74
	v_permlane16_swap_b32_e32 v73, v75
	global_store_dwordx4 v[146:147], v[80:83], off
	global_store_dwordx4 v[146:147], v[72:75], off offset:256
	s_cmp_eq_u32 s10, 64
	s_cbranch_scc1 .Lp7e_nopad
	v_cvt_pk_bf16_f32 v64, v64, v65
	v_cvt_pk_bf16_f32 v65, v66, v67
	v_cvt_pk_bf16_f32 v66, v60, v61
	v_cvt_pk_bf16_f32 v67, v62, v63
	v_cvt_pk_bf16_f32 v56, v56, v57
	v_cvt_pk_bf16_f32 v57, v58, v59
	v_cvt_pk_bf16_f32 v58, v52, v53
	v_cvt_pk_bf16_f32 v59, v54, v55
	s_nop 1
	v_permlane16_swap_b32_e32 v64, v66
	v_permlane16_swap_b32_e32 v65, v67
	v_permlane16_swap_b32_e32 v56, v58
	v_permlane16_swap_b32_e32 v57, v59
	global_store_dwordx4 v[148:149], v[64:67], off
	global_store_dwordx4 v[148:149], v[56:59], off offset:256
	v_cvt_pk_bf16_f32 v48, v48, v49
	v_cvt_pk_bf16_f32 v49, v50, v51
	v_cvt_pk_bf16_f32 v50, v44, v45
	v_cvt_pk_bf16_f32 v51, v46, v47
	v_cvt_pk_bf16_f32 v40, v40, v41
	v_cvt_pk_bf16_f32 v41, v42, v43
	v_cvt_pk_bf16_f32 v42, v36, v37
	v_cvt_pk_bf16_f32 v43, v38, v39
	s_nop 1
	v_permlane16_swap_b32_e32 v48, v50
	v_permlane16_swap_b32_e32 v49, v51
	v_permlane16_swap_b32_e32 v40, v42
	v_permlane16_swap_b32_e32 v41, v43
	global_store_dwordx4 v[150:151], v[48:51], off
	global_store_dwordx4 v[150:151], v[40:43], off offset:256
	v_cvt_pk_bf16_f32 v32, v32, v33
	v_cvt_pk_bf16_f32 v33, v34, v35
	v_cvt_pk_bf16_f32 v34, v28, v29
	v_cvt_pk_bf16_f32 v35, v30, v31
	v_cvt_pk_bf16_f32 v24, v24, v25
	v_cvt_pk_bf16_f32 v25, v26, v27
	v_cvt_pk_bf16_f32 v26, v20, v21
	v_cvt_pk_bf16_f32 v27, v22, v23
	s_nop 1
	v_permlane16_swap_b32_e32 v32, v34
	v_permlane16_swap_b32_e32 v33, v35
	v_permlane16_swap_b32_e32 v24, v26
	v_permlane16_swap_b32_e32 v25, v27
	global_store_dwordx4 v[152:153], v[32:35], off
	global_store_dwordx4 v[152:153], v[24:27], off offset:256
	v_cvt_pk_bf16_f32 v16, v16, v17
	v_cvt_pk_bf16_f32 v17, v18, v19
	v_cvt_pk_bf16_f32 v18, v12, v13
	v_cvt_pk_bf16_f32 v19, v14, v15
	v_cvt_pk_bf16_f32 v8, v8, v9
	v_cvt_pk_bf16_f32 v9, v10, v11
	v_cvt_pk_bf16_f32 v10, v4, v5
	v_cvt_pk_bf16_f32 v11, v6, v7
	s_nop 1
	v_permlane16_swap_b32_e32 v16, v18
	v_permlane16_swap_b32_e32 v17, v19
	v_permlane16_swap_b32_e32 v8, v10
	v_permlane16_swap_b32_e32 v9, v11
	global_store_dwordx4 v[154:155], v[16:19], off
	global_store_dwordx4 v[154:155], v[8:11], off offset:256
.Lp7e_nopad:
	s_mov_b64 s[8:9], exec
	s_branch .LBB0_534

.LBB0_911:
	v_lshl_add_u32 v2, s38, 8, v212
	s_waitcnt lgkmcnt(0)
	v_lshl_or_b32 v132, s74, 8, v214
	v_bfe_u32 v138, v214, 2, 1
	v_mul_u32_u24_e32 v138, 24, v138
	v_lshl_add_u32 v136, v132, 1, v138
	v_mov_b32_e32 v137, 0
	v_ashrrev_i32_e32 v3, 31, v2
	v_lshlrev_b64 v[140:141], 12, v[2:3]
	v_lshl_add_u64 v[140:141], s[26:27], 0, v[140:141]
	v_lshl_add_u64 v[140:141], v[140:141], 0, v[136:137]
	v_or_b32_e32 v142, 16, v2
	v_ashrrev_i32_e32 v143, 31, v142
	v_lshlrev_b64 v[142:143], 12, v[142:143]
	v_lshl_add_u64 v[142:143], s[26:27], 0, v[142:143]
	v_lshl_add_u64 v[142:143], v[142:143], 0, v[136:137]
	v_or_b32_e32 v144, 32, v2
	v_ashrrev_i32_e32 v145, 31, v144
	v_lshlrev_b64 v[144:145], 12, v[144:145]
	v_lshl_add_u64 v[144:145], s[26:27], 0, v[144:145]
	v_lshl_add_u64 v[144:145], v[144:145], 0, v[136:137]
	v_or_b32_e32 v146, 48, v2
	v_ashrrev_i32_e32 v147, 31, v146
	v_lshlrev_b64 v[146:147], 12, v[146:147]
	v_lshl_add_u64 v[146:147], s[26:27], 0, v[146:147]
	v_lshl_add_u64 v[146:147], v[146:147], 0, v[136:137]
	v_lshl_add_u64 v[148:149], v[140:141], 0, s[10:11]
	v_lshl_add_u64 v[150:151], v[142:143], 0, s[10:11]
	v_lshl_add_u64 v[152:153], v[144:145], 0, s[10:11]
	v_lshl_add_u64 v[154:155], v[146:147], 0, s[10:11]
	s_nop 7
	v_cvt_pk_bf16_f32 v128, v128, v129
	v_cvt_pk_bf16_f32 v129, v130, v131
	v_cvt_pk_bf16_f32 v130, v124, v125
	v_cvt_pk_bf16_f32 v131, v126, v127
	v_cvt_pk_bf16_f32 v116, v116, v117
	v_cvt_pk_bf16_f32 v117, v118, v119
	v_cvt_pk_bf16_f32 v118, v108, v109
	v_cvt_pk_bf16_f32 v119, v110, v111
	s_nop 1
	v_permlane16_swap_b32_e32 v128, v130
	v_permlane16_swap_b32_e32 v129, v131
	v_permlane16_swap_b32_e32 v116, v118
	v_permlane16_swap_b32_e32 v117, v119
	global_store_dwordx4 v[140:141], v[128:131], off
	global_store_dwordx4 v[140:141], v[116:119], off offset:256
	v_cvt_pk_bf16_f32 v120, v120, v121
	v_cvt_pk_bf16_f32 v121, v122, v123
	v_cvt_pk_bf16_f32 v122, v112, v113
	v_cvt_pk_bf16_f32 v123, v114, v115
	v_cvt_pk_bf16_f32 v100, v100, v101
	v_cvt_pk_bf16_f32 v101, v102, v103
	v_cvt_pk_bf16_f32 v102, v92, v93
	v_cvt_pk_bf16_f32 v103, v94, v95
	s_nop 1
	v_permlane16_swap_b32_e32 v120, v122
	v_permlane16_swap_b32_e32 v121, v123
	v_permlane16_swap_b32_e32 v100, v102
	v_permlane16_swap_b32_e32 v101, v103
	global_store_dwordx4 v[142:143], v[120:123], off
	global_store_dwordx4 v[142:143], v[100:103], off offset:256
	v_cvt_pk_bf16_f32 v104, v104, v105
	v_cvt_pk_bf16_f32 v105, v106, v107
	v_cvt_pk_bf16_f32 v106, v96, v97
	v_cvt_pk_bf16_f32 v107, v98, v99
	v_cvt_pk_bf16_f32 v84, v84, v85
	v_cvt_pk_bf16_f32 v85, v86, v87
	v_cvt_pk_bf16_f32 v86, v76, v77
	v_cvt_pk_bf16_f32 v87, v78, v79
	s_nop 1
	v_permlane16_swap_b32_e32 v104, v106
	v_permlane16_swap_b32_e32 v105, v107
	v_permlane16_swap_b32_e32 v84, v86
	v_permlane16_swap_b32_e32 v85, v87
	global_store_dwordx4 v[144:145], v[104:107], off
	global_store_dwordx4 v[144:145], v[84:87], off offset:256
	v_cvt_pk_bf16_f32 v88, v88, v89
	v_cvt_pk_bf16_f32 v89, v90, v91
	v_cvt_pk_bf16_f32 v90, v80, v81
	v_cvt_pk_bf16_f32 v91, v82, v83
	v_cvt_pk_bf16_f32 v72, v72, v73
	v_cvt_pk_bf16_f32 v73, v74, v75
	v_cvt_pk_bf16_f32 v74, v68, v69
	v_cvt_pk_bf16_f32 v75, v70, v71
	s_nop 1
	v_permlane16_swap_b32_e32 v88, v90
	v_permlane16_swap_b32_e32 v89, v91
	v_permlane16_swap_b32_e32 v72, v74
	v_permlane16_swap_b32_e32 v73, v75
	global_store_dwordx4 v[146:147], v[88:91], off
	global_store_dwordx4 v[146:147], v[72:75], off offset:256
	s_cmp_eq_u32 s38, 64
	s_cbranch_scc1 .Lp9e_nopad
	v_cvt_pk_bf16_f32 v64, v64, v65
	v_cvt_pk_bf16_f32 v65, v66, v67
	v_cvt_pk_bf16_f32 v66, v60, v61
	v_cvt_pk_bf16_f32 v67, v62, v63
	v_cvt_pk_bf16_f32 v56, v56, v57
	v_cvt_pk_bf16_f32 v57, v58, v59
	v_cvt_pk_bf16_f32 v58, v48, v49
	v_cvt_pk_bf16_f32 v59, v50, v51
	s_nop 1
	v_permlane16_swap_b32_e32 v64, v66
	v_permlane16_swap_b32_e32 v65, v67
	v_permlane16_swap_b32_e32 v56, v58
	v_permlane16_swap_b32_e32 v57, v59
	global_store_dwordx4 v[148:149], v[64:67], off
	global_store_dwordx4 v[148:149], v[56:59], off offset:256
	v_cvt_pk_bf16_f32 v52, v52, v53
	v_cvt_pk_bf16_f32 v53, v54, v55
	v_cvt_pk_bf16_f32 v54, v44, v45
	v_cvt_pk_bf16_f32 v55, v46, v47
	v_cvt_pk_bf16_f32 v40, v40, v41
	v_cvt_pk_bf16_f32 v41, v42, v43
	v_cvt_pk_bf16_f32 v42, v32, v33
	v_cvt_pk_bf16_f32 v43, v34, v35
	s_nop 1
	v_permlane16_swap_b32_e32 v52, v54
	v_permlane16_swap_b32_e32 v53, v55
	v_permlane16_swap_b32_e32 v40, v42
	v_permlane16_swap_b32_e32 v41, v43
	global_store_dwordx4 v[150:151], v[52:55], off
	global_store_dwordx4 v[150:151], v[40:43], off offset:256
	v_cvt_pk_bf16_f32 v36, v36, v37
	v_cvt_pk_bf16_f32 v37, v38, v39
	v_cvt_pk_bf16_f32 v38, v28, v29
	v_cvt_pk_bf16_f32 v39, v30, v31
	v_cvt_pk_bf16_f32 v24, v24, v25
	v_cvt_pk_bf16_f32 v25, v26, v27
	v_cvt_pk_bf16_f32 v26, v16, v17
	v_cvt_pk_bf16_f32 v27, v18, v19
	s_nop 1
	v_permlane16_swap_b32_e32 v36, v38
	v_permlane16_swap_b32_e32 v37, v39
	v_permlane16_swap_b32_e32 v24, v26
	v_permlane16_swap_b32_e32 v25, v27
	global_store_dwordx4 v[152:153], v[36:39], off
	global_store_dwordx4 v[152:153], v[24:27], off offset:256
	v_cvt_pk_bf16_f32 v20, v20, v21
	v_cvt_pk_bf16_f32 v21, v22, v23
	v_cvt_pk_bf16_f32 v22, v12, v13
	v_cvt_pk_bf16_f32 v23, v14, v15
	v_cvt_pk_bf16_f32 v8, v8, v9
	v_cvt_pk_bf16_f32 v9, v10, v11
	v_cvt_pk_bf16_f32 v10, v4, v5
	v_cvt_pk_bf16_f32 v11, v6, v7
	s_nop 1
	v_permlane16_swap_b32_e32 v20, v22
	v_permlane16_swap_b32_e32 v21, v23
	v_permlane16_swap_b32_e32 v8, v10
	v_permlane16_swap_b32_e32 v9, v11
	global_store_dwordx4 v[154:155], v[20:23], off
	global_store_dwordx4 v[154:155], v[8:11], off offset:256
.Lp9e_nopad:
	s_and_b64 vcc, exec, s[20:21]
	s_mov_b32 s74, s73
	s_mov_b32 s38, s22
	s_mov_b64 s[52:53], s[28:29]
	s_mov_b64 s[8:9], s[30:31]
	s_cbranch_vccnz .LBB0_928
